# baseline (speedup 1.0000x reference)
.LBB0_164:
	v_mov_b32_e32 v14, v0
	v_mov_b32_e32 v15, v0
	v_sub_u32_e32 v231, v1, v130
	v_mov_b32_e32 v1, v0
	v_mov_b32_e32 v2, v0
	v_mov_b32_e32 v3, v0
	v_mov_b32_e32 v4, v0
	v_mov_b32_e32 v5, v0
	v_mov_b32_e32 v6, v0
	v_mov_b32_e32 v7, v0
	v_mov_b32_e32 v8, v0
	v_mov_b32_e32 v9, v0
	v_mov_b32_e32 v10, v0
	v_mov_b32_e32 v11, v0
	v_mov_b32_e32 v12, v0
	v_mov_b32_e32 v13, v0
	v_mov_b64_e32 v[64:65], v[14:15]
	v_mov_b64_e32 v[48:49], v[14:15]
	v_mov_b64_e32 v[32:33], v[14:15]
	s_lshl_b32 s33, s10, 1
	v_mov_b64_e32 v[62:63], v[12:13]
	v_mov_b64_e32 v[60:61], v[10:11]
	v_mov_b64_e32 v[58:59], v[8:9]
	v_mov_b64_e32 v[56:57], v[6:7]
	v_mov_b64_e32 v[54:55], v[4:5]
	v_mov_b64_e32 v[52:53], v[2:3]
	v_mov_b64_e32 v[50:51], v[0:1]
	v_mov_b64_e32 v[46:47], v[12:13]
	v_mov_b64_e32 v[44:45], v[10:11]
	v_mov_b64_e32 v[42:43], v[8:9]
	v_mov_b64_e32 v[40:41], v[6:7]
	v_mov_b64_e32 v[38:39], v[4:5]
	v_mov_b64_e32 v[36:37], v[2:3]
	v_mov_b64_e32 v[34:35], v[0:1]
	v_mov_b64_e32 v[30:31], v[12:13]
	v_mov_b64_e32 v[28:29], v[10:11]
	v_mov_b64_e32 v[26:27], v[8:9]
	v_mov_b64_e32 v[24:25], v[6:7]
	v_mov_b64_e32 v[22:23], v[4:5]
	v_mov_b64_e32 v[20:21], v[2:3]
	v_mov_b64_e32 v[18:19], v[0:1]
	v_mov_b64_e32 v[16:17], v[14:15]
	s_xor_b64 s[2:3], s[8:9], -1
	s_add_i32 s79, s33, 2
	s_mov_b32 s99, 0
	v_mov_b32_e32 v233, 0xf149f2ca
	v_mov_b32_e32 v232, 0
	s_movk_i32 s98, 0xff
	v_mov_b64_e32 v[200:201], v[198:199]
	v_mov_b64_e32 v[14:15], v[12:13]
	v_mov_b64_e32 v[12:13], v[10:11]
	v_mov_b64_e32 v[10:11], v[8:9]
	v_mov_b64_e32 v[8:9], v[6:7]
	v_mov_b64_e32 v[6:7], v[4:5]
	v_mov_b64_e32 v[4:5], v[2:3]
	v_mov_b64_e32 v[2:3], v[0:1]
	s_waitcnt lgkmcnt(0)
	s_barrier
	s_cmp_lt_u32 s97, 64
	s_cbranch_scc0 .Lattn_entry_b
	s_cmp_lt_u32 s99, s33
	s_cselect_b64 s[38:39], -1, 0
	s_cmp_ge_u32 s99, s33
	s_cbranch_scc1 .LBB0_167
	s_branch .LBB0_166

.Lattn_sl0:
	ds_read_b64_tr_b16 v[94:95], v153 offset:0x3200
	ds_read_b64_tr_b16 v[96:97], v153 offset:0x3a00
	s_waitcnt lgkmcnt(6)
	v_mfma_f32_32x32x16_bf16 v[34:49], v[66:69], v[82:85], v[34:49]
	ds_read_b64_tr_b16 v[82:83], v153 offset:0x400
	ds_read_b64_tr_b16 v[84:85], v153 offset:0xc00
	s_waitcnt lgkmcnt(6)
	v_mfma_f32_32x32x16_bf16 v[34:49], v[70:73], v[86:89], v[34:49]
	ds_read_b64_tr_b16 v[86:87], v153 offset:0x1400
	ds_read_b64_tr_b16 v[88:89], v153 offset:0x1c00
	s_waitcnt lgkmcnt(6)
	v_mfma_f32_32x32x16_bf16 v[34:49], v[74:77], v[90:93], v[34:49]
	ds_read_b64_tr_b16 v[90:91], v153 offset:0x2400
	ds_read_b64_tr_b16 v[92:93], v153 offset:0x2c00
	s_waitcnt lgkmcnt(6)
	v_mfma_f32_32x32x16_bf16 v[34:49], v[78:81], v[94:97], v[34:49]
	ds_read_b64_tr_b16 v[94:95], v153 offset:0x3400
	ds_read_b64_tr_b16 v[96:97], v153 offset:0x3c00
	s_waitcnt lgkmcnt(6)
	v_mfma_f32_32x32x16_bf16 v[18:33], v[66:69], v[82:85], v[18:33]
	ds_read_b64_tr_b16 v[82:83], v153 offset:0x600
	ds_read_b64_tr_b16 v[84:85], v153 offset:0xe00
	s_waitcnt lgkmcnt(6)
	v_mfma_f32_32x32x16_bf16 v[18:33], v[70:73], v[86:89], v[18:33]
	ds_read_b64_tr_b16 v[86:87], v153 offset:0x1600
	ds_read_b64_tr_b16 v[88:89], v153 offset:0x1e00
	s_waitcnt lgkmcnt(6)
	v_mfma_f32_32x32x16_bf16 v[18:33], v[74:77], v[90:93], v[18:33]
	ds_read_b64_tr_b16 v[90:91], v153 offset:0x2600
	ds_read_b64_tr_b16 v[92:93], v153 offset:0x2e00
	s_waitcnt lgkmcnt(6)
	v_mfma_f32_32x32x16_bf16 v[18:33], v[78:81], v[94:97], v[18:33]
	ds_read_b64_tr_b16 v[94:95], v153 offset:0x3600
	ds_read_b64_tr_b16 v[96:97], v153 offset:0x3e00
	s_waitcnt lgkmcnt(6)
	v_mfma_f32_32x32x16_bf16 v[2:17], v[66:69], v[82:85], v[2:17]
	s_andn2_b64 vcc, exec, s[72:73]
	s_waitcnt lgkmcnt(0)
	s_barrier
	s_waitcnt lgkmcnt(4)
	v_mfma_f32_32x32x16_bf16 v[2:17], v[70:73], v[86:89], v[2:17]
	s_waitcnt lgkmcnt(2)
	v_mfma_f32_32x32x16_bf16 v[2:17], v[74:77], v[90:93], v[2:17]
	s_waitcnt lgkmcnt(0)
	v_mfma_f32_32x32x16_bf16 v[2:17], v[78:81], v[94:97], v[2:17]

.Lattn_sl2:
	ds_read_b64_tr_b16 v[94:95], v153 offset:0xb200
	ds_read_b64_tr_b16 v[96:97], v153 offset:0xba00
	s_waitcnt lgkmcnt(6)
	v_mfma_f32_32x32x16_bf16 v[34:49], v[66:69], v[82:85], v[34:49]
	ds_read_b64_tr_b16 v[82:83], v153 offset:0x8400
	ds_read_b64_tr_b16 v[84:85], v153 offset:0x8c00
	s_waitcnt lgkmcnt(6)
	v_mfma_f32_32x32x16_bf16 v[34:49], v[70:73], v[86:89], v[34:49]
	ds_read_b64_tr_b16 v[86:87], v153 offset:0x9400
	ds_read_b64_tr_b16 v[88:89], v153 offset:0x9c00
	s_waitcnt lgkmcnt(6)
	v_mfma_f32_32x32x16_bf16 v[34:49], v[74:77], v[90:93], v[34:49]
	ds_read_b64_tr_b16 v[90:91], v153 offset:0xa400
	ds_read_b64_tr_b16 v[92:93], v153 offset:0xac00
	s_waitcnt lgkmcnt(6)
	v_mfma_f32_32x32x16_bf16 v[34:49], v[78:81], v[94:97], v[34:49]
	ds_read_b64_tr_b16 v[94:95], v153 offset:0xb400
	ds_read_b64_tr_b16 v[96:97], v153 offset:0xbc00
	s_waitcnt lgkmcnt(6)
	v_mfma_f32_32x32x16_bf16 v[18:33], v[66:69], v[82:85], v[18:33]
	ds_read_b64_tr_b16 v[82:83], v153 offset:0x8600
	ds_read_b64_tr_b16 v[84:85], v153 offset:0x8e00
	s_waitcnt lgkmcnt(6)
	v_mfma_f32_32x32x16_bf16 v[18:33], v[70:73], v[86:89], v[18:33]
	ds_read_b64_tr_b16 v[86:87], v153 offset:0x9600
	ds_read_b64_tr_b16 v[88:89], v153 offset:0x9e00
	s_waitcnt lgkmcnt(6)
	v_mfma_f32_32x32x16_bf16 v[18:33], v[74:77], v[90:93], v[18:33]
	ds_read_b64_tr_b16 v[90:91], v153 offset:0xa600
	ds_read_b64_tr_b16 v[92:93], v153 offset:0xae00
	s_waitcnt lgkmcnt(6)
	v_mfma_f32_32x32x16_bf16 v[18:33], v[78:81], v[94:97], v[18:33]
	ds_read_b64_tr_b16 v[94:95], v153 offset:0xb600
	ds_read_b64_tr_b16 v[96:97], v153 offset:0xbe00
	s_waitcnt lgkmcnt(6)
	v_mfma_f32_32x32x16_bf16 v[2:17], v[66:69], v[82:85], v[2:17]
	s_andn2_b64 vcc, exec, s[38:39]
	s_waitcnt lgkmcnt(0)
	s_barrier
	s_waitcnt lgkmcnt(4)
	v_mfma_f32_32x32x16_bf16 v[2:17], v[70:73], v[86:89], v[2:17]
	s_waitcnt lgkmcnt(2)
	v_mfma_f32_32x32x16_bf16 v[2:17], v[74:77], v[90:93], v[2:17]
	s_waitcnt lgkmcnt(0)
	v_mfma_f32_32x32x16_bf16 v[2:17], v[78:81], v[94:97], v[2:17]

.LBB0_207:
	s_add_i32 s10, s99, 4
	s_mov_b64 s[8:9], 0x180000
	s_addk_i32 s98, 0x100
	v_lshl_add_u64 v[200:201], v[200:201], 0, s[8:9]
	s_cmp_gt_u32 s10, s33
	v_add_u32_e32 v231, 0xffffff00, v231
	s_cbranch_scc0 .LBB0_165
	s_branch .Lattn_epi

.Lattn_b_175:
	v_cndmask_b32_e64 v233, v234, v233, s[8:9]
	v_mul_f32_e32 v206, 0xbe38aa3b, v233
	v_fmamk_f32 v82, v82, 0x3e38aa3b, v206
	v_fmamk_f32 v83, v83, 0x3e38aa3b, v206
	v_fmamk_f32 v84, v84, 0x3e38aa3b, v206
	v_fmamk_f32 v85, v85, 0x3e38aa3b, v206
	v_fmamk_f32 v86, v86, 0x3e38aa3b, v206
	v_fmamk_f32 v87, v87, 0x3e38aa3b, v206
	v_fmamk_f32 v88, v88, 0x3e38aa3b, v206
	v_fmamk_f32 v89, v89, 0x3e38aa3b, v206
	v_fmamk_f32 v90, v90, 0x3e38aa3b, v206
	v_fmamk_f32 v91, v91, 0x3e38aa3b, v206
	v_fmamk_f32 v92, v92, 0x3e38aa3b, v206
	v_fmamk_f32 v93, v93, 0x3e38aa3b, v206
	v_fmamk_f32 v94, v94, 0x3e38aa3b, v206
	v_fmamk_f32 v95, v95, 0x3e38aa3b, v206
	v_fmamk_f32 v96, v96, 0x3e38aa3b, v206
	v_fmamk_f32 v97, v97, 0x3e38aa3b, v206
	v_fmamk_f32 v66, v66, 0x3e38aa3b, v206
	v_fmamk_f32 v67, v67, 0x3e38aa3b, v206
	v_fmamk_f32 v68, v68, 0x3e38aa3b, v206
	v_fmamk_f32 v69, v69, 0x3e38aa3b, v206
	v_fmamk_f32 v70, v70, 0x3e38aa3b, v206
	v_fmamk_f32 v71, v71, 0x3e38aa3b, v206
	v_fmamk_f32 v72, v72, 0x3e38aa3b, v206
	v_fmamk_f32 v73, v73, 0x3e38aa3b, v206
	v_fmamk_f32 v74, v74, 0x3e38aa3b, v206
	v_fmamk_f32 v75, v75, 0x3e38aa3b, v206
	v_fmamk_f32 v76, v76, 0x3e38aa3b, v206
	v_fmamk_f32 v77, v77, 0x3e38aa3b, v206
	v_fmamk_f32 v78, v78, 0x3e38aa3b, v206
	v_fmamk_f32 v79, v79, 0x3e38aa3b, v206
	v_fmamk_f32 v80, v80, 0x3e38aa3b, v206
	v_fmac_f32_e32 v206, 0x3e38aa3b, v81
	v_exp_f32_e32 v81, v82
	v_exp_f32_e32 v82, v83
	v_exp_f32_e32 v83, v84
	v_exp_f32_e32 v84, v85
	v_exp_f32_e32 v85, v86
	v_exp_f32_e32 v86, v87
	v_exp_f32_e32 v87, v88
	v_exp_f32_e32 v88, v89
	v_exp_f32_e32 v89, v90
	v_exp_f32_e32 v90, v91
	v_exp_f32_e32 v91, v92
	v_exp_f32_e32 v92, v93
	v_exp_f32_e32 v93, v94
	v_exp_f32_e32 v94, v95
	v_exp_f32_e32 v95, v96
	v_exp_f32_e32 v96, v97
	v_exp_f32_e32 v97, v66
	v_add_f32_e32 v66, 0, v81
	v_add_f32_e32 v66, v82, v66
	v_add_f32_e32 v66, v83, v66
	v_add_f32_e32 v66, v84, v66
	v_add_f32_e32 v66, v85, v66
	v_add_f32_e32 v66, v86, v66
	v_add_f32_e32 v66, v87, v66
	v_add_f32_e32 v66, v88, v66
	v_add_f32_e32 v66, v89, v66
	v_add_f32_e32 v66, v90, v66
	v_add_f32_e32 v66, v91, v66
	v_add_f32_e32 v66, v92, v66
	v_add_f32_e32 v66, v93, v66
	v_exp_f32_e32 v212, v67
	v_add_f32_e32 v66, v94, v66
	v_exp_f32_e32 v213, v68
	v_add_f32_e32 v66, v95, v66
	v_exp_f32_e32 v214, v69
	v_add_f32_e32 v66, v96, v66
	v_exp_f32_e32 v215, v70
	v_add_f32_e32 v66, v97, v66
	v_exp_f32_e32 v236, v71
	v_add_f32_e32 v66, v212, v66
	v_exp_f32_e32 v237, v72
	v_add_f32_e32 v66, v213, v66
	v_exp_f32_e32 v238, v73
	v_add_f32_e32 v66, v214, v66
	v_exp_f32_e32 v239, v74
	v_add_f32_e32 v66, v215, v66
	v_exp_f32_e32 v240, v75
	v_add_f32_e32 v66, v236, v66
	v_exp_f32_e32 v241, v76
	v_add_f32_e32 v66, v237, v66
	v_exp_f32_e32 v242, v77
	v_add_f32_e32 v66, v238, v66
	v_exp_f32_e32 v243, v78
	v_add_f32_e32 v66, v239, v66
	v_exp_f32_e32 v244, v79
	v_add_f32_e32 v66, v240, v66
	v_exp_f32_e32 v245, v80
	v_add_f32_e32 v66, v241, v66
	v_exp_f32_e32 v206, v206
	v_add_f32_e32 v66, v242, v66
	v_add_f32_e32 v66, v243, v66
	v_add_f32_e32 v66, v244, v66
	v_add_f32_e32 v66, v245, v66
	v_add_f32_e32 v234, v206, v66
	v_mov_b32_e32 v235, v234
	s_nop 1
	v_permlane32_swap_b32_e32 v234, v235
	v_cvt_pk_bf16_f32 v66, v81, v82
	v_cvt_pk_bf16_f32 v67, v83, v84
	v_cvt_pk_bf16_f32 v68, v85, v86
	v_cvt_pk_bf16_f32 v69, v87, v88
	v_cvt_pk_bf16_f32 v70, v89, v90
	v_cvt_pk_bf16_f32 v71, v91, v92
	v_cvt_pk_bf16_f32 v72, v93, v94
	v_cvt_pk_bf16_f32 v73, v95, v96
	v_cvt_pk_bf16_f32 v74, v97, v212
	v_cvt_pk_bf16_f32 v75, v213, v214
	v_cvt_pk_bf16_f32 v76, v215, v236
	v_cvt_pk_bf16_f32 v77, v237, v238
	v_cvt_pk_bf16_f32 v78, v239, v240
	v_cvt_pk_bf16_f32 v79, v241, v242
	v_cvt_pk_bf16_f32 v80, v243, v244
	v_cvt_pk_bf16_f32 v81, v245, v206
	s_nop 0
	v_permlane32_swap_b32_e32 v66, v68
	v_permlane32_swap_b32_e32 v67, v69
	v_permlane32_swap_b32_e32 v70, v72
	v_permlane32_swap_b32_e32 v71, v73
	v_permlane32_swap_b32_e32 v74, v76
	v_permlane32_swap_b32_e32 v75, v77
	v_permlane32_swap_b32_e32 v78, v80
	v_permlane32_swap_b32_e32 v79, v81
	s_waitcnt lgkmcnt(0)
	s_barrier
	ds_read_b64_tr_b16 v[82:83], v153 offset:0
	ds_read_b64_tr_b16 v[84:85], v153 offset:0x800
	ds_read_b64_tr_b16 v[86:87], v153 offset:0x1000
	ds_read_b64_tr_b16 v[88:89], v153 offset:0x1800
	ds_read_b64_tr_b16 v[90:91], v153 offset:0x2000
	ds_read_b64_tr_b16 v[92:93], v153 offset:0x2800
	ds_read_b64_tr_b16 v[94:95], v153 offset:0x3000
	ds_read_b64_tr_b16 v[96:97], v153 offset:0x3800
	s_nop 0
	s_waitcnt lgkmcnt(6)
	v_mfma_f32_32x32x16_bf16 v[50:65], v[66:69], v[82:85], v[50:65]
	ds_read_b64_tr_b16 v[82:83], v153 offset:0x200
	ds_read_b64_tr_b16 v[84:85], v153 offset:0xa00
	s_waitcnt lgkmcnt(6)
	v_mfma_f32_32x32x16_bf16 v[50:65], v[70:73], v[86:89], v[50:65]
	ds_read_b64_tr_b16 v[86:87], v153 offset:0x1200
	ds_read_b64_tr_b16 v[88:89], v153 offset:0x1a00
	s_waitcnt lgkmcnt(6)
	v_mfma_f32_32x32x16_bf16 v[50:65], v[74:77], v[90:93], v[50:65]
	ds_read_b64_tr_b16 v[90:91], v153 offset:0x2200
	ds_read_b64_tr_b16 v[92:93], v153 offset:0x2a00
	s_waitcnt lgkmcnt(6)
	v_mfma_f32_32x32x16_bf16 v[50:65], v[78:81], v[94:97], v[50:65]
	s_andn2_b64 vcc, exec, s[38:39]
	s_cbranch_vccnz .Lattn_b_sw0
	v_add_u32_e32 v250, s84, v157
	s_waitcnt vmcnt(3)
	ds_write_b128 v224, v[114:117] offset:32768
	s_waitcnt vmcnt(1)
	ds_write_b128 v224, v[122:125] offset:40960
	ds_write_b128 v250, v[118:121]
	v_add_u32_e32 v250, s84, v155
	s_waitcnt vmcnt(0)
	ds_write_b128 v250, v[126:129]

.Lattn_b_185:
	v_cndmask_b32_e64 v233, v237, v233, s[8:9]
	v_mul_f32_e32 v206, 0xbe38aa3b, v233
	v_fmamk_f32 v82, v82, 0x3e38aa3b, v206
	v_fmamk_f32 v83, v83, 0x3e38aa3b, v206
	v_fmamk_f32 v84, v84, 0x3e38aa3b, v206
	v_fmamk_f32 v85, v85, 0x3e38aa3b, v206
	v_fmamk_f32 v86, v86, 0x3e38aa3b, v206
	v_fmamk_f32 v87, v87, 0x3e38aa3b, v206
	v_fmamk_f32 v88, v88, 0x3e38aa3b, v206
	v_fmamk_f32 v89, v89, 0x3e38aa3b, v206
	v_fmamk_f32 v90, v90, 0x3e38aa3b, v206
	v_fmamk_f32 v91, v91, 0x3e38aa3b, v206
	v_fmamk_f32 v92, v92, 0x3e38aa3b, v206
	v_fmamk_f32 v93, v93, 0x3e38aa3b, v206
	v_fmamk_f32 v94, v94, 0x3e38aa3b, v206
	v_fmamk_f32 v95, v95, 0x3e38aa3b, v206
	v_fmamk_f32 v96, v96, 0x3e38aa3b, v206
	v_fmamk_f32 v97, v97, 0x3e38aa3b, v206
	v_fmamk_f32 v66, v66, 0x3e38aa3b, v206
	v_fmamk_f32 v67, v67, 0x3e38aa3b, v206
	v_fmamk_f32 v68, v68, 0x3e38aa3b, v206
	v_fmamk_f32 v69, v69, 0x3e38aa3b, v206
	v_fmamk_f32 v70, v70, 0x3e38aa3b, v206
	v_fmamk_f32 v71, v71, 0x3e38aa3b, v206
	v_fmamk_f32 v72, v72, 0x3e38aa3b, v206
	v_fmamk_f32 v73, v73, 0x3e38aa3b, v206
	v_fmamk_f32 v74, v74, 0x3e38aa3b, v206
	v_fmamk_f32 v75, v75, 0x3e38aa3b, v206
	v_fmamk_f32 v76, v76, 0x3e38aa3b, v206
	v_fmamk_f32 v77, v77, 0x3e38aa3b, v206
	v_fmamk_f32 v78, v78, 0x3e38aa3b, v206
	v_fmamk_f32 v79, v79, 0x3e38aa3b, v206
	v_fmamk_f32 v80, v80, 0x3e38aa3b, v206
	v_fmac_f32_e32 v206, 0x3e38aa3b, v81
	v_exp_f32_e32 v81, v82
	v_exp_f32_e32 v82, v83
	v_exp_f32_e32 v83, v84
	v_exp_f32_e32 v84, v85
	v_exp_f32_e32 v85, v86
	v_exp_f32_e32 v86, v87
	v_exp_f32_e32 v87, v88
	v_exp_f32_e32 v88, v89
	v_exp_f32_e32 v89, v90
	v_exp_f32_e32 v90, v91
	v_exp_f32_e32 v91, v92
	v_exp_f32_e32 v92, v93
	v_exp_f32_e32 v93, v94
	v_exp_f32_e32 v94, v95
	v_exp_f32_e32 v95, v96
	v_exp_f32_e32 v96, v97
	v_add_f32_e32 v97, v234, v235
	v_fmac_f32_e32 v97, v232, v1
	v_exp_f32_e32 v1, v66
	v_add_f32_e32 v66, 0, v81
	v_add_f32_e32 v66, v82, v66
	v_add_f32_e32 v66, v83, v66
	v_add_f32_e32 v66, v84, v66
	v_add_f32_e32 v66, v85, v66
	v_add_f32_e32 v66, v86, v66
	v_add_f32_e32 v66, v87, v66
	v_add_f32_e32 v66, v88, v66
	v_add_f32_e32 v66, v89, v66
	v_add_f32_e32 v66, v90, v66
	v_add_f32_e32 v66, v91, v66
	v_add_f32_e32 v66, v92, v66
	v_add_f32_e32 v66, v93, v66
	v_exp_f32_e32 v212, v67
	v_add_f32_e32 v66, v94, v66
	v_exp_f32_e32 v213, v68
	v_add_f32_e32 v66, v95, v66
	v_exp_f32_e32 v214, v69
	v_add_f32_e32 v66, v96, v66
	v_exp_f32_e32 v215, v70
	v_add_f32_e32 v66, v1, v66
	v_exp_f32_e32 v234, v71
	v_add_f32_e32 v66, v212, v66
	v_exp_f32_e32 v235, v72
	v_add_f32_e32 v66, v213, v66
	v_exp_f32_e32 v237, v73
	v_add_f32_e32 v66, v214, v66
	v_exp_f32_e32 v238, v74
	v_add_f32_e32 v66, v215, v66
	v_exp_f32_e32 v239, v75
	v_add_f32_e32 v66, v234, v66
	v_exp_f32_e32 v240, v76
	v_add_f32_e32 v66, v235, v66
	v_exp_f32_e32 v241, v77
	v_add_f32_e32 v66, v237, v66
	v_exp_f32_e32 v242, v78
	v_add_f32_e32 v66, v238, v66
	v_exp_f32_e32 v243, v79
	v_add_f32_e32 v66, v239, v66
	v_exp_f32_e32 v244, v80
	v_add_f32_e32 v66, v240, v66
	v_exp_f32_e32 v206, v206
	v_add_f32_e32 v66, v241, v66
	v_add_f32_e32 v66, v242, v66
	v_add_f32_e32 v66, v243, v66
	v_add_f32_e32 v66, v244, v66
	v_add_f32_e32 v66, v206, v66
	v_mov_b32_e32 v67, v66
	s_nop 1
	v_permlane32_swap_b32_e32 v66, v67
	v_add_f32_e32 v232, v66, v67
	v_fmac_f32_e32 v232, v97, v236
	v_cvt_pk_bf16_f32 v66, v81, v82
	v_cvt_pk_bf16_f32 v67, v83, v84
	v_cvt_pk_bf16_f32 v68, v85, v86
	v_cvt_pk_bf16_f32 v69, v87, v88
	v_cvt_pk_bf16_f32 v70, v89, v90
	v_cvt_pk_bf16_f32 v71, v91, v92
	v_cvt_pk_bf16_f32 v72, v93, v94
	v_cvt_pk_bf16_f32 v73, v95, v96
	v_cvt_pk_bf16_f32 v74, v1, v212
	v_cvt_pk_bf16_f32 v75, v213, v214
	v_cvt_pk_bf16_f32 v76, v215, v234
	v_cvt_pk_bf16_f32 v77, v235, v237
	v_cvt_pk_bf16_f32 v78, v238, v239
	v_cvt_pk_bf16_f32 v79, v240, v241
	v_cvt_pk_bf16_f32 v80, v242, v243
	v_cvt_pk_bf16_f32 v81, v244, v206
	s_nop 0
	v_permlane32_swap_b32_e32 v66, v68
	v_permlane32_swap_b32_e32 v67, v69
	v_permlane32_swap_b32_e32 v70, v72
	v_permlane32_swap_b32_e32 v71, v73
	v_permlane32_swap_b32_e32 v74, v76
	v_permlane32_swap_b32_e32 v75, v77
	v_permlane32_swap_b32_e32 v78, v80
	v_permlane32_swap_b32_e32 v79, v81
	s_waitcnt lgkmcnt(0)
	s_barrier
	ds_read_b64_tr_b16 v[82:83], v153 offset:0x4000
	ds_read_b64_tr_b16 v[84:85], v153 offset:0x4800
	ds_read_b64_tr_b16 v[86:87], v153 offset:0x5000
	ds_read_b64_tr_b16 v[88:89], v153 offset:0x5800
	ds_read_b64_tr_b16 v[90:91], v153 offset:0x6000
	ds_read_b64_tr_b16 v[92:93], v153 offset:0x6800
	ds_read_b64_tr_b16 v[94:95], v153 offset:0x7000
	ds_read_b64_tr_b16 v[96:97], v153 offset:0x7800
	s_nop 0
	s_waitcnt lgkmcnt(6)
	v_mfma_f32_32x32x16_bf16 v[50:65], v[66:69], v[82:85], v[50:65]
	ds_read_b64_tr_b16 v[82:83], v153 offset:0x4200
	ds_read_b64_tr_b16 v[84:85], v153 offset:0x4a00
	s_waitcnt lgkmcnt(6)
	v_mfma_f32_32x32x16_bf16 v[50:65], v[70:73], v[86:89], v[50:65]
	ds_read_b64_tr_b16 v[86:87], v153 offset:0x5200
	ds_read_b64_tr_b16 v[88:89], v153 offset:0x5a00
	s_waitcnt lgkmcnt(6)
	v_mfma_f32_32x32x16_bf16 v[50:65], v[74:77], v[90:93], v[50:65]
	ds_read_b64_tr_b16 v[90:91], v153 offset:0x6200
	ds_read_b64_tr_b16 v[92:93], v153 offset:0x6a00
	s_waitcnt lgkmcnt(6)
	v_mfma_f32_32x32x16_bf16 v[50:65], v[78:81], v[94:97], v[50:65]
	s_andn2_b64 vcc, exec, s[72:73]
	s_cbranch_vccnz .Lattn_b_sw1
	v_add_u32_e32 v250, s88, v157
	s_waitcnt vmcnt(3)
	ds_write_b128 v224, v[114:117] offset:49152
	s_waitcnt vmcnt(1)
	ds_write_b128 v224, v[122:125] offset:57344
	ds_write_b128 v250, v[118:121]
	v_add_u32_e32 v250, s88, v155
	s_waitcnt vmcnt(0)
	ds_write_b128 v250, v[126:129]

.Lattn_b_sl1:
	ds_read_b64_tr_b16 v[94:95], v153 offset:0x7200
	ds_read_b64_tr_b16 v[96:97], v153 offset:0x7a00
	s_waitcnt lgkmcnt(6)
	v_mfma_f32_32x32x16_bf16 v[34:49], v[66:69], v[82:85], v[34:49]
	ds_read_b64_tr_b16 v[82:83], v153 offset:0x4400
	ds_read_b64_tr_b16 v[84:85], v153 offset:0x4c00
	s_waitcnt lgkmcnt(6)
	v_mfma_f32_32x32x16_bf16 v[34:49], v[70:73], v[86:89], v[34:49]
	ds_read_b64_tr_b16 v[86:87], v153 offset:0x5400
	ds_read_b64_tr_b16 v[88:89], v153 offset:0x5c00
	s_waitcnt lgkmcnt(6)
	v_mfma_f32_32x32x16_bf16 v[34:49], v[74:77], v[90:93], v[34:49]
	ds_read_b64_tr_b16 v[90:91], v153 offset:0x6400
	ds_read_b64_tr_b16 v[92:93], v153 offset:0x6c00
	s_waitcnt lgkmcnt(6)
	v_mfma_f32_32x32x16_bf16 v[34:49], v[78:81], v[94:97], v[34:49]
	ds_read_b64_tr_b16 v[94:95], v153 offset:0x7400
	ds_read_b64_tr_b16 v[96:97], v153 offset:0x7c00
	s_waitcnt lgkmcnt(6)
	v_mfma_f32_32x32x16_bf16 v[18:33], v[66:69], v[82:85], v[18:33]
	ds_read_b64_tr_b16 v[82:83], v153 offset:0x4600
	ds_read_b64_tr_b16 v[84:85], v153 offset:0x4e00
	s_waitcnt lgkmcnt(6)
	v_mfma_f32_32x32x16_bf16 v[18:33], v[70:73], v[86:89], v[18:33]
	ds_read_b64_tr_b16 v[86:87], v153 offset:0x5600
	ds_read_b64_tr_b16 v[88:89], v153 offset:0x5e00
	s_waitcnt lgkmcnt(6)
	v_mfma_f32_32x32x16_bf16 v[18:33], v[74:77], v[90:93], v[18:33]
	ds_read_b64_tr_b16 v[90:91], v153 offset:0x6600
	ds_read_b64_tr_b16 v[92:93], v153 offset:0x6e00
	s_waitcnt lgkmcnt(6)
	v_mfma_f32_32x32x16_bf16 v[18:33], v[78:81], v[94:97], v[18:33]
	ds_read_b64_tr_b16 v[94:95], v153 offset:0x7600
	ds_read_b64_tr_b16 v[96:97], v153 offset:0x7e00
	s_waitcnt lgkmcnt(6)
	v_mfma_f32_32x32x16_bf16 v[2:17], v[66:69], v[82:85], v[2:17]
	s_andn2_b64 vcc, exec, s[38:39]
	s_waitcnt lgkmcnt(4)
	v_mfma_f32_32x32x16_bf16 v[2:17], v[70:73], v[86:89], v[2:17]
	s_waitcnt lgkmcnt(2)
	v_mfma_f32_32x32x16_bf16 v[2:17], v[74:77], v[90:93], v[2:17]
	s_waitcnt lgkmcnt(0)
	v_mfma_f32_32x32x16_bf16 v[2:17], v[78:81], v[94:97], v[2:17]
	s_cbranch_vccnz .Lattn_b_207

.Lattn_b_196:
	v_cndmask_b32_e64 v233, v234, v233, s[8:9]
	v_mul_f32_e32 v206, 0xbe38aa3b, v233
	v_fmamk_f32 v82, v82, 0x3e38aa3b, v206
	v_fmamk_f32 v83, v83, 0x3e38aa3b, v206
	v_fmamk_f32 v84, v84, 0x3e38aa3b, v206
	v_fmamk_f32 v85, v85, 0x3e38aa3b, v206
	v_fmamk_f32 v86, v86, 0x3e38aa3b, v206
	v_fmamk_f32 v87, v87, 0x3e38aa3b, v206
	v_fmamk_f32 v88, v88, 0x3e38aa3b, v206
	v_fmamk_f32 v89, v89, 0x3e38aa3b, v206
	v_fmamk_f32 v90, v90, 0x3e38aa3b, v206
	v_fmamk_f32 v91, v91, 0x3e38aa3b, v206
	v_fmamk_f32 v92, v92, 0x3e38aa3b, v206
	v_fmamk_f32 v93, v93, 0x3e38aa3b, v206
	v_fmamk_f32 v94, v94, 0x3e38aa3b, v206
	v_fmamk_f32 v95, v95, 0x3e38aa3b, v206
	v_fmamk_f32 v96, v96, 0x3e38aa3b, v206
	v_fmamk_f32 v97, v97, 0x3e38aa3b, v206
	v_fmamk_f32 v66, v66, 0x3e38aa3b, v206
	v_fmamk_f32 v67, v67, 0x3e38aa3b, v206
	v_fmamk_f32 v68, v68, 0x3e38aa3b, v206
	v_fmamk_f32 v69, v69, 0x3e38aa3b, v206
	v_fmamk_f32 v70, v70, 0x3e38aa3b, v206
	v_fmamk_f32 v71, v71, 0x3e38aa3b, v206
	v_fmamk_f32 v72, v72, 0x3e38aa3b, v206
	v_fmamk_f32 v73, v73, 0x3e38aa3b, v206
	v_fmamk_f32 v74, v74, 0x3e38aa3b, v206
	v_fmamk_f32 v75, v75, 0x3e38aa3b, v206
	v_fmamk_f32 v76, v76, 0x3e38aa3b, v206
	v_fmamk_f32 v77, v77, 0x3e38aa3b, v206
	v_fmamk_f32 v78, v78, 0x3e38aa3b, v206
	v_fmamk_f32 v79, v79, 0x3e38aa3b, v206
	v_fmamk_f32 v80, v80, 0x3e38aa3b, v206
	v_fmac_f32_e32 v206, 0x3e38aa3b, v81
	v_exp_f32_e32 v81, v82
	v_exp_f32_e32 v82, v83
	v_exp_f32_e32 v83, v84
	v_exp_f32_e32 v84, v85
	v_exp_f32_e32 v85, v86
	v_exp_f32_e32 v86, v87
	v_exp_f32_e32 v87, v88
	v_exp_f32_e32 v88, v89
	v_exp_f32_e32 v89, v90
	v_exp_f32_e32 v90, v91
	v_exp_f32_e32 v91, v92
	v_exp_f32_e32 v92, v93
	v_exp_f32_e32 v93, v94
	v_exp_f32_e32 v94, v95
	v_exp_f32_e32 v95, v96
	v_exp_f32_e32 v96, v97
	v_exp_f32_e32 v97, v66
	v_add_f32_e32 v66, 0, v81
	v_add_f32_e32 v66, v82, v66
	v_add_f32_e32 v66, v83, v66
	v_add_f32_e32 v66, v84, v66
	v_add_f32_e32 v66, v85, v66
	v_add_f32_e32 v66, v86, v66
	v_add_f32_e32 v66, v87, v66
	v_add_f32_e32 v66, v88, v66
	v_add_f32_e32 v66, v89, v66
	v_add_f32_e32 v66, v90, v66
	v_add_f32_e32 v66, v91, v66
	v_add_f32_e32 v66, v92, v66
	v_add_f32_e32 v66, v93, v66
	v_exp_f32_e32 v212, v67
	v_add_f32_e32 v66, v94, v66
	v_exp_f32_e32 v213, v68
	v_add_f32_e32 v66, v95, v66
	v_exp_f32_e32 v214, v69
	v_add_f32_e32 v66, v96, v66
	v_exp_f32_e32 v215, v70
	v_add_f32_e32 v66, v97, v66
	v_exp_f32_e32 v236, v71
	v_add_f32_e32 v66, v212, v66
	v_exp_f32_e32 v237, v72
	v_add_f32_e32 v66, v213, v66
	v_exp_f32_e32 v238, v73
	v_add_f32_e32 v66, v214, v66
	v_exp_f32_e32 v239, v74
	v_add_f32_e32 v66, v215, v66
	v_exp_f32_e32 v240, v75
	v_add_f32_e32 v66, v236, v66
	v_exp_f32_e32 v241, v76
	v_add_f32_e32 v66, v237, v66
	v_exp_f32_e32 v242, v77
	v_add_f32_e32 v66, v238, v66
	v_exp_f32_e32 v243, v78
	v_add_f32_e32 v66, v239, v66
	v_exp_f32_e32 v244, v79
	v_add_f32_e32 v66, v240, v66
	v_exp_f32_e32 v245, v80
	v_add_f32_e32 v66, v241, v66
	v_exp_f32_e32 v206, v206
	v_add_f32_e32 v66, v242, v66
	v_add_f32_e32 v66, v243, v66
	v_add_f32_e32 v66, v244, v66
	v_add_f32_e32 v66, v245, v66
	v_add_f32_e32 v234, v206, v66
	v_mov_b32_e32 v235, v234
	s_nop 1
	v_permlane32_swap_b32_e32 v234, v235
	v_cvt_pk_bf16_f32 v66, v81, v82
	v_cvt_pk_bf16_f32 v67, v83, v84
	v_cvt_pk_bf16_f32 v68, v85, v86
	v_cvt_pk_bf16_f32 v69, v87, v88
	v_cvt_pk_bf16_f32 v70, v89, v90
	v_cvt_pk_bf16_f32 v71, v91, v92
	v_cvt_pk_bf16_f32 v72, v93, v94
	v_cvt_pk_bf16_f32 v73, v95, v96
	v_cvt_pk_bf16_f32 v74, v97, v212
	v_cvt_pk_bf16_f32 v75, v213, v214
	v_cvt_pk_bf16_f32 v76, v215, v236
	v_cvt_pk_bf16_f32 v77, v237, v238
	v_cvt_pk_bf16_f32 v78, v239, v240
	v_cvt_pk_bf16_f32 v79, v241, v242
	v_cvt_pk_bf16_f32 v80, v243, v244
	v_cvt_pk_bf16_f32 v81, v245, v206
	s_nop 0
	v_permlane32_swap_b32_e32 v66, v68
	v_permlane32_swap_b32_e32 v67, v69
	v_permlane32_swap_b32_e32 v70, v72
	v_permlane32_swap_b32_e32 v71, v73
	v_permlane32_swap_b32_e32 v74, v76
	v_permlane32_swap_b32_e32 v75, v77
	v_permlane32_swap_b32_e32 v78, v80
	v_permlane32_swap_b32_e32 v79, v81
	s_waitcnt lgkmcnt(0)
	s_barrier
	ds_read_b64_tr_b16 v[82:83], v153 offset:0x8000
	ds_read_b64_tr_b16 v[84:85], v153 offset:0x8800
	ds_read_b64_tr_b16 v[86:87], v153 offset:0x9000
	ds_read_b64_tr_b16 v[88:89], v153 offset:0x9800
	ds_read_b64_tr_b16 v[90:91], v153 offset:0xa000
	ds_read_b64_tr_b16 v[92:93], v153 offset:0xa800
	ds_read_b64_tr_b16 v[94:95], v153 offset:0xb000
	ds_read_b64_tr_b16 v[96:97], v153 offset:0xb800
	s_nop 0
	s_waitcnt lgkmcnt(6)
	v_mfma_f32_32x32x16_bf16 v[50:65], v[66:69], v[82:85], v[50:65]
	ds_read_b64_tr_b16 v[82:83], v153 offset:0x8200
	ds_read_b64_tr_b16 v[84:85], v153 offset:0x8a00
	s_waitcnt lgkmcnt(6)
	v_mfma_f32_32x32x16_bf16 v[50:65], v[70:73], v[86:89], v[50:65]
	ds_read_b64_tr_b16 v[86:87], v153 offset:0x9200
	ds_read_b64_tr_b16 v[88:89], v153 offset:0x9a00
	s_waitcnt lgkmcnt(6)
	v_mfma_f32_32x32x16_bf16 v[50:65], v[74:77], v[90:93], v[50:65]
	ds_read_b64_tr_b16 v[90:91], v153 offset:0xa200
	ds_read_b64_tr_b16 v[92:93], v153 offset:0xaa00
	s_waitcnt lgkmcnt(6)
	v_mfma_f32_32x32x16_bf16 v[50:65], v[78:81], v[94:97], v[50:65]
	s_andn2_b64 vcc, exec, s[72:73]
	s_cbranch_vccnz .Lattn_b_sw2
	s_waitcnt vmcnt(3)
	ds_write_b128 v224, v[114:117]
	s_waitcnt vmcnt(1)
	ds_write_b128 v224, v[122:125] offset:8192
	ds_write_b128 v173, v[118:121]
	s_waitcnt vmcnt(0)
	ds_write_b128 v175, v[126:129]

.Lattn_b_206:
	v_cndmask_b32_e64 v233, v237, v233, s[8:9]
	v_mul_f32_e32 v206, 0xbe38aa3b, v233
	v_fmamk_f32 v82, v82, 0x3e38aa3b, v206
	v_fmamk_f32 v83, v83, 0x3e38aa3b, v206
	v_fmamk_f32 v84, v84, 0x3e38aa3b, v206
	v_fmamk_f32 v85, v85, 0x3e38aa3b, v206
	v_fmamk_f32 v86, v86, 0x3e38aa3b, v206
	v_fmamk_f32 v87, v87, 0x3e38aa3b, v206
	v_fmamk_f32 v88, v88, 0x3e38aa3b, v206
	v_fmamk_f32 v89, v89, 0x3e38aa3b, v206
	v_fmamk_f32 v90, v90, 0x3e38aa3b, v206
	v_fmamk_f32 v91, v91, 0x3e38aa3b, v206
	v_fmamk_f32 v92, v92, 0x3e38aa3b, v206
	v_fmamk_f32 v93, v93, 0x3e38aa3b, v206
	v_fmamk_f32 v94, v94, 0x3e38aa3b, v206
	v_fmamk_f32 v95, v95, 0x3e38aa3b, v206
	v_fmamk_f32 v96, v96, 0x3e38aa3b, v206
	v_fmamk_f32 v97, v97, 0x3e38aa3b, v206
	v_fmamk_f32 v66, v66, 0x3e38aa3b, v206
	v_fmamk_f32 v67, v67, 0x3e38aa3b, v206
	v_fmamk_f32 v68, v68, 0x3e38aa3b, v206
	v_fmamk_f32 v69, v69, 0x3e38aa3b, v206
	v_fmamk_f32 v70, v70, 0x3e38aa3b, v206
	v_fmamk_f32 v71, v71, 0x3e38aa3b, v206
	v_fmamk_f32 v72, v72, 0x3e38aa3b, v206
	v_fmamk_f32 v73, v73, 0x3e38aa3b, v206
	v_fmamk_f32 v74, v74, 0x3e38aa3b, v206
	v_fmamk_f32 v75, v75, 0x3e38aa3b, v206
	v_fmamk_f32 v76, v76, 0x3e38aa3b, v206
	v_fmamk_f32 v77, v77, 0x3e38aa3b, v206
	v_fmamk_f32 v78, v78, 0x3e38aa3b, v206
	v_fmamk_f32 v79, v79, 0x3e38aa3b, v206
	v_fmamk_f32 v80, v80, 0x3e38aa3b, v206
	v_fmac_f32_e32 v206, 0x3e38aa3b, v81
	v_exp_f32_e32 v81, v82
	v_exp_f32_e32 v82, v83
	v_exp_f32_e32 v83, v84
	v_exp_f32_e32 v84, v85
	v_exp_f32_e32 v85, v86
	v_exp_f32_e32 v86, v87
	v_exp_f32_e32 v87, v88
	v_exp_f32_e32 v88, v89
	v_exp_f32_e32 v89, v90
	v_exp_f32_e32 v90, v91
	v_exp_f32_e32 v91, v92
	v_exp_f32_e32 v92, v93
	v_exp_f32_e32 v93, v94
	v_exp_f32_e32 v94, v95
	v_exp_f32_e32 v95, v96
	v_exp_f32_e32 v96, v97
	v_add_f32_e32 v97, v234, v235
	v_fmac_f32_e32 v97, v232, v1
	v_exp_f32_e32 v1, v66
	v_add_f32_e32 v66, 0, v81
	v_add_f32_e32 v66, v82, v66
	v_add_f32_e32 v66, v83, v66
	v_add_f32_e32 v66, v84, v66
	v_add_f32_e32 v66, v85, v66
	v_add_f32_e32 v66, v86, v66
	v_add_f32_e32 v66, v87, v66
	v_add_f32_e32 v66, v88, v66
	v_add_f32_e32 v66, v89, v66
	v_add_f32_e32 v66, v90, v66
	v_add_f32_e32 v66, v91, v66
	v_add_f32_e32 v66, v92, v66
	v_add_f32_e32 v66, v93, v66
	v_exp_f32_e32 v212, v67
	v_add_f32_e32 v66, v94, v66
	v_exp_f32_e32 v213, v68
	v_add_f32_e32 v66, v95, v66
	v_exp_f32_e32 v214, v69
	v_add_f32_e32 v66, v96, v66
	v_exp_f32_e32 v215, v70
	v_add_f32_e32 v66, v1, v66
	v_exp_f32_e32 v234, v71
	v_add_f32_e32 v66, v212, v66
	v_exp_f32_e32 v235, v72
	v_add_f32_e32 v66, v213, v66
	v_exp_f32_e32 v237, v73
	v_add_f32_e32 v66, v214, v66
	v_exp_f32_e32 v238, v74
	v_add_f32_e32 v66, v215, v66
	v_exp_f32_e32 v239, v75
	v_add_f32_e32 v66, v234, v66
	v_exp_f32_e32 v240, v76
	v_add_f32_e32 v66, v235, v66
	v_exp_f32_e32 v241, v77
	v_add_f32_e32 v66, v237, v66
	v_exp_f32_e32 v242, v78
	v_add_f32_e32 v66, v238, v66
	v_exp_f32_e32 v243, v79
	v_add_f32_e32 v66, v239, v66
	v_exp_f32_e32 v244, v80
	v_add_f32_e32 v66, v240, v66
	v_exp_f32_e32 v206, v206
	v_add_f32_e32 v66, v241, v66
	v_add_f32_e32 v66, v242, v66
	v_add_f32_e32 v66, v243, v66
	v_add_f32_e32 v66, v244, v66
	v_add_f32_e32 v66, v206, v66
	v_mov_b32_e32 v67, v66
	s_nop 1
	v_permlane32_swap_b32_e32 v66, v67
	v_add_f32_e32 v232, v66, v67
	v_fmac_f32_e32 v232, v97, v236
	v_cvt_pk_bf16_f32 v66, v81, v82
	v_cvt_pk_bf16_f32 v67, v83, v84
	v_cvt_pk_bf16_f32 v68, v85, v86
	v_cvt_pk_bf16_f32 v69, v87, v88
	v_cvt_pk_bf16_f32 v70, v89, v90
	v_cvt_pk_bf16_f32 v71, v91, v92
	v_cvt_pk_bf16_f32 v72, v93, v94
	v_cvt_pk_bf16_f32 v73, v95, v96
	v_cvt_pk_bf16_f32 v74, v1, v212
	v_cvt_pk_bf16_f32 v75, v213, v214
	v_cvt_pk_bf16_f32 v76, v215, v234
	v_cvt_pk_bf16_f32 v77, v235, v237
	v_cvt_pk_bf16_f32 v78, v238, v239
	v_cvt_pk_bf16_f32 v79, v240, v241
	v_cvt_pk_bf16_f32 v80, v242, v243
	v_cvt_pk_bf16_f32 v81, v244, v206
	s_nop 0
	v_permlane32_swap_b32_e32 v66, v68
	v_permlane32_swap_b32_e32 v67, v69
	v_permlane32_swap_b32_e32 v70, v72
	v_permlane32_swap_b32_e32 v71, v73
	v_permlane32_swap_b32_e32 v74, v76
	v_permlane32_swap_b32_e32 v75, v77
	v_permlane32_swap_b32_e32 v78, v80
	v_permlane32_swap_b32_e32 v79, v81
	s_waitcnt lgkmcnt(0)
	s_barrier
	ds_read_b64_tr_b16 v[82:83], v153 offset:0xc000
	ds_read_b64_tr_b16 v[84:85], v153 offset:0xc800
	ds_read_b64_tr_b16 v[86:87], v153 offset:0xd000
	ds_read_b64_tr_b16 v[88:89], v153 offset:0xd800
	ds_read_b64_tr_b16 v[90:91], v153 offset:0xe000
	ds_read_b64_tr_b16 v[92:93], v153 offset:0xe800
	ds_read_b64_tr_b16 v[94:95], v153 offset:0xf000
	ds_read_b64_tr_b16 v[96:97], v153 offset:0xf800
	s_nop 0
	s_waitcnt lgkmcnt(6)
	v_mfma_f32_32x32x16_bf16 v[50:65], v[66:69], v[82:85], v[50:65]
	ds_read_b64_tr_b16 v[82:83], v153 offset:0xc200
	ds_read_b64_tr_b16 v[84:85], v153 offset:0xca00
	s_waitcnt lgkmcnt(6)
	v_mfma_f32_32x32x16_bf16 v[50:65], v[70:73], v[86:89], v[50:65]
	ds_read_b64_tr_b16 v[86:87], v153 offset:0xd200
	ds_read_b64_tr_b16 v[88:89], v153 offset:0xda00
	s_waitcnt lgkmcnt(6)
	v_mfma_f32_32x32x16_bf16 v[50:65], v[74:77], v[90:93], v[50:65]
	ds_read_b64_tr_b16 v[90:91], v153 offset:0xe200
	ds_read_b64_tr_b16 v[92:93], v153 offset:0xea00
	s_waitcnt lgkmcnt(6)
	v_mfma_f32_32x32x16_bf16 v[50:65], v[78:81], v[94:97], v[50:65]
	s_andn2_b64 vcc, exec, s[38:39]
	s_cbranch_vccnz .Lattn_b_sw3
	s_waitcnt vmcnt(3)
	ds_write_b128 v224, v[114:117] offset:16384
	s_waitcnt vmcnt(1)
	ds_write_b128 v224, v[122:125] offset:24576
	ds_write_b128 v229, v[118:121]
	s_waitcnt vmcnt(0)
	ds_write_b128 v230, v[126:129]

.Lattn_b_sl3:
	ds_read_b64_tr_b16 v[94:95], v153 offset:0xf200
	ds_read_b64_tr_b16 v[96:97], v153 offset:0xfa00
	s_waitcnt lgkmcnt(6)
	v_mfma_f32_32x32x16_bf16 v[34:49], v[66:69], v[82:85], v[34:49]
	ds_read_b64_tr_b16 v[82:83], v153 offset:0xc400
	ds_read_b64_tr_b16 v[84:85], v153 offset:0xcc00
	s_waitcnt lgkmcnt(6)
	v_mfma_f32_32x32x16_bf16 v[34:49], v[70:73], v[86:89], v[34:49]
	ds_read_b64_tr_b16 v[86:87], v153 offset:0xd400
	ds_read_b64_tr_b16 v[88:89], v153 offset:0xdc00
	s_waitcnt lgkmcnt(6)
	v_mfma_f32_32x32x16_bf16 v[34:49], v[74:77], v[90:93], v[34:49]
	ds_read_b64_tr_b16 v[90:91], v153 offset:0xe400
	ds_read_b64_tr_b16 v[92:93], v153 offset:0xec00
	s_waitcnt lgkmcnt(6)
	v_mfma_f32_32x32x16_bf16 v[34:49], v[78:81], v[94:97], v[34:49]
	ds_read_b64_tr_b16 v[94:95], v153 offset:0xf400
	ds_read_b64_tr_b16 v[96:97], v153 offset:0xfc00
	s_waitcnt lgkmcnt(6)
	v_mfma_f32_32x32x16_bf16 v[18:33], v[66:69], v[82:85], v[18:33]
	ds_read_b64_tr_b16 v[82:83], v153 offset:0xc600
	ds_read_b64_tr_b16 v[84:85], v153 offset:0xce00
	s_waitcnt lgkmcnt(6)
	v_mfma_f32_32x32x16_bf16 v[18:33], v[70:73], v[86:89], v[18:33]
	ds_read_b64_tr_b16 v[86:87], v153 offset:0xd600
	ds_read_b64_tr_b16 v[88:89], v153 offset:0xde00
	s_waitcnt lgkmcnt(6)
	v_mfma_f32_32x32x16_bf16 v[18:33], v[74:77], v[90:93], v[18:33]
	ds_read_b64_tr_b16 v[90:91], v153 offset:0xe600
	ds_read_b64_tr_b16 v[92:93], v153 offset:0xee00
	s_waitcnt lgkmcnt(6)
	v_mfma_f32_32x32x16_bf16 v[18:33], v[78:81], v[94:97], v[18:33]
	ds_read_b64_tr_b16 v[94:95], v153 offset:0xf600
	ds_read_b64_tr_b16 v[96:97], v153 offset:0xfe00
	s_waitcnt lgkmcnt(6)
	v_mfma_f32_32x32x16_bf16 v[2:17], v[66:69], v[82:85], v[2:17]
	s_waitcnt lgkmcnt(4)
	v_mfma_f32_32x32x16_bf16 v[2:17], v[70:73], v[86:89], v[2:17]
	s_waitcnt lgkmcnt(2)
	v_mfma_f32_32x32x16_bf16 v[2:17], v[74:77], v[90:93], v[2:17]
	s_waitcnt lgkmcnt(0)
	v_mfma_f32_32x32x16_bf16 v[2:17], v[78:81], v[94:97], v[2:17]

.Lattn_epi:
	s_setprio 0
	s_and_saveexec_b64 s[8:9], s[4:5]
	ds_write_b32 v159, v232
	s_or_b64 exec, exec, s[8:9]
	s_waitcnt lgkmcnt(0)
	ds_read_b128 v[70:73], v161
	ds_read_b128 v[66:69], v161 offset:32
	s_mov_b32 s98, s0
	s_mov_b32 s79, s94
	s_mov_b32 s99, s1
	s_waitcnt lgkmcnt(1)
	v_div_scale_f32 v1, s[8:9], v70, v70, 1.0
	v_rcp_f32_e32 v74, v1
	s_nop 0
	v_fma_f32 v75, -v1, v74, 1.0
	v_fmac_f32_e32 v74, v75, v74
	v_div_scale_f32 v75, vcc, 1.0, v70, 1.0
	v_mul_f32_e32 v76, v75, v74
	v_fma_f32 v77, -v1, v76, v75
	v_fmac_f32_e32 v76, v77, v74
	v_fma_f32 v1, -v1, v76, v75
	v_div_fmas_f32 v1, v1, v74, v76
	v_div_fixup_f32 v96, v1, v70, 1.0
	v_div_scale_f32 v1, s[8:9], v71, v71, 1.0
	v_rcp_f32_e32 v70, v1
	s_nop 0
	v_fma_f32 v74, -v1, v70, 1.0
	v_fmac_f32_e32 v70, v74, v70
	v_div_scale_f32 v74, vcc, 1.0, v71, 1.0
	v_mul_f32_e32 v75, v74, v70
	v_fma_f32 v76, -v1, v75, v74
	v_fmac_f32_e32 v75, v76, v70
	v_fma_f32 v1, -v1, v75, v74
	v_div_fmas_f32 v1, v1, v70, v75
	v_div_fixup_f32 v94, v1, v71, 1.0
	v_div_scale_f32 v1, s[8:9], v72, v72, 1.0
	v_rcp_f32_e32 v70, v1
	s_nop 0
	v_fma_f32 v71, -v1, v70, 1.0
	v_fmac_f32_e32 v70, v71, v70
	v_div_scale_f32 v71, vcc, 1.0, v72, 1.0
	v_mul_f32_e32 v74, v71, v70
	v_fma_f32 v75, -v1, v74, v71
	v_fmac_f32_e32 v74, v75, v70
	v_fma_f32 v1, -v1, v74, v71
	v_div_fmas_f32 v1, v1, v70, v74
	v_div_fixup_f32 v92, v1, v72, 1.0
	v_div_scale_f32 v1, s[8:9], v73, v73, 1.0
	v_rcp_f32_e32 v70, v1
	s_nop 0
	v_fma_f32 v71, -v1, v70, 1.0
	v_fmac_f32_e32 v70, v71, v70
	v_div_scale_f32 v71, vcc, 1.0, v73, 1.0
	v_mul_f32_e32 v72, v71, v70
	v_fma_f32 v74, -v1, v72, v71
	v_fmac_f32_e32 v72, v74, v70
	v_fma_f32 v1, -v1, v72, v71
	v_div_fmas_f32 v1, v1, v70, v72
	v_div_fixup_f32 v90, v1, v73, 1.0
	s_waitcnt lgkmcnt(0)
	v_div_scale_f32 v1, s[8:9], v66, v66, 1.0
	v_rcp_f32_e32 v70, v1
	s_nop 0
	v_fma_f32 v71, -v1, v70, 1.0
	v_fmac_f32_e32 v70, v71, v70
	v_div_scale_f32 v71, vcc, 1.0, v66, 1.0
	v_mul_f32_e32 v72, v71, v70
	v_fma_f32 v73, -v1, v72, v71
	v_fmac_f32_e32 v72, v73, v70
	v_fma_f32 v1, -v1, v72, v71
	v_div_fmas_f32 v1, v1, v70, v72
	v_div_fixup_f32 v88, v1, v66, 1.0
	v_div_scale_f32 v1, s[8:9], v67, v67, 1.0
	v_rcp_f32_e32 v66, v1
	s_nop 0
	v_fma_f32 v70, -v1, v66, 1.0
	v_fmac_f32_e32 v66, v70, v66
	v_div_scale_f32 v70, vcc, 1.0, v67, 1.0
	v_mul_f32_e32 v71, v70, v66
	v_fma_f32 v72, -v1, v71, v70
	v_fmac_f32_e32 v71, v72, v66
	v_fma_f32 v1, -v1, v71, v70
	v_div_fmas_f32 v1, v1, v66, v71
	v_div_fixup_f32 v86, v1, v67, 1.0
	v_div_scale_f32 v1, s[8:9], v68, v68, 1.0
	v_rcp_f32_e32 v66, v1
	s_nop 0
	v_fma_f32 v67, -v1, v66, 1.0
	v_fmac_f32_e32 v66, v67, v66
	v_div_scale_f32 v67, vcc, 1.0, v68, 1.0
	v_mul_f32_e32 v70, v67, v66
	v_fma_f32 v71, -v1, v70, v67
	v_fmac_f32_e32 v70, v71, v66
	v_fma_f32 v1, -v1, v70, v67
	v_div_fmas_f32 v1, v1, v66, v70
	v_div_fixup_f32 v84, v1, v68, 1.0
	v_div_scale_f32 v1, s[8:9], v69, v69, 1.0
	v_rcp_f32_e32 v66, v1
	s_nop 0
	v_fma_f32 v67, -v1, v66, 1.0
	v_fmac_f32_e32 v66, v67, v66
	v_div_scale_f32 v67, vcc, 1.0, v69, 1.0
	v_mul_f32_e32 v68, v67, v66
	v_fma_f32 v70, -v1, v68, v67
	v_fmac_f32_e32 v68, v70, v66
	v_fma_f32 v1, -v1, v68, v67
	v_div_fmas_f32 v1, v1, v66, v68
	v_div_fixup_f32 v82, v1, v69, 1.0
	ds_read_b128 v[66:69], v161 offset:64
	s_waitcnt lgkmcnt(0)
	v_div_scale_f32 v1, s[8:9], v66, v66, 1.0
	v_rcp_f32_e32 v70, v1
	s_nop 0
	v_fma_f32 v71, -v1, v70, 1.0
	v_fmac_f32_e32 v70, v71, v70
	v_div_scale_f32 v71, vcc, 1.0, v66, 1.0
	v_mul_f32_e32 v72, v71, v70
	v_fma_f32 v73, -v1, v72, v71
	v_fmac_f32_e32 v72, v73, v70
	v_fma_f32 v1, -v1, v72, v71
	v_div_fmas_f32 v1, v1, v70, v72
	v_div_fixup_f32 v80, v1, v66, 1.0
	v_div_scale_f32 v1, s[8:9], v67, v67, 1.0
	v_rcp_f32_e32 v66, v1
	s_nop 0
	v_fma_f32 v70, -v1, v66, 1.0
	v_fmac_f32_e32 v66, v70, v66
	v_div_scale_f32 v70, vcc, 1.0, v67, 1.0
	v_mul_f32_e32 v71, v70, v66
	v_fma_f32 v72, -v1, v71, v70
	v_fmac_f32_e32 v71, v72, v66
	v_fma_f32 v1, -v1, v71, v70
	v_div_fmas_f32 v1, v1, v66, v71
	v_div_fixup_f32 v76, v1, v67, 1.0
	v_div_scale_f32 v1, s[8:9], v68, v68, 1.0
	v_rcp_f32_e32 v66, v1
	s_nop 0
	v_fma_f32 v67, -v1, v66, 1.0
	v_fmac_f32_e32 v66, v67, v66
	v_div_scale_f32 v67, vcc, 1.0, v68, 1.0
	v_mul_f32_e32 v70, v67, v66
	v_fma_f32 v71, -v1, v70, v67
	v_fmac_f32_e32 v70, v71, v66
	v_fma_f32 v1, -v1, v70, v67
	v_div_fmas_f32 v1, v1, v66, v70
	v_div_fixup_f32 v72, v1, v68, 1.0
	v_div_scale_f32 v1, s[8:9], v69, v69, 1.0
	v_rcp_f32_e32 v66, v1
	s_nop 0
	v_fma_f32 v67, -v1, v66, 1.0
	v_fmac_f32_e32 v66, v67, v66
	v_div_scale_f32 v67, vcc, 1.0, v69, 1.0
	v_mul_f32_e32 v68, v67, v66
	v_fma_f32 v70, -v1, v68, v67
	v_fmac_f32_e32 v68, v70, v66
	v_fma_f32 v1, -v1, v68, v67
	v_div_fmas_f32 v1, v1, v66, v68
	v_div_fixup_f32 v70, v1, v69, 1.0
	ds_read_b128 v[66:69], v161 offset:96
	s_waitcnt lgkmcnt(0)
	v_div_scale_f32 v1, s[8:9], v66, v66, 1.0
	v_rcp_f32_e32 v71, v1
	s_nop 0
	v_fma_f32 v73, -v1, v71, 1.0
	v_fmac_f32_e32 v71, v73, v71
	v_div_scale_f32 v73, vcc, 1.0, v66, 1.0
	v_mul_f32_e32 v74, v73, v71
	v_fma_f32 v75, -v1, v74, v73
	v_fmac_f32_e32 v74, v75, v71
	v_fma_f32 v1, -v1, v74, v73
	v_div_fmas_f32 v1, v1, v71, v74
	v_div_fixup_f32 v78, v1, v66, 1.0
	v_div_scale_f32 v1, s[8:9], v67, v67, 1.0
	v_rcp_f32_e32 v66, v1
	s_nop 0
	v_fma_f32 v71, -v1, v66, 1.0
	v_fmac_f32_e32 v66, v71, v66
	v_div_scale_f32 v71, vcc, 1.0, v67, 1.0
	v_mul_f32_e32 v73, v71, v66
	v_fma_f32 v74, -v1, v73, v71
	v_fmac_f32_e32 v73, v74, v66
	v_fma_f32 v1, -v1, v73, v71
	v_div_fmas_f32 v1, v1, v66, v73
	v_div_fixup_f32 v74, v1, v67, 1.0
	v_div_scale_f32 v1, s[8:9], v68, v68, 1.0
	v_rcp_f32_e32 v66, v1
	s_nop 0
	v_fma_f32 v67, -v1, v66, 1.0
	v_fmac_f32_e32 v66, v67, v66
	v_div_scale_f32 v67, vcc, 1.0, v68, 1.0
	v_mul_f32_e32 v71, v67, v66
	v_fma_f32 v73, -v1, v71, v67
	v_fmac_f32_e32 v71, v73, v66
	v_fma_f32 v1, -v1, v71, v67
	v_div_fmas_f32 v1, v1, v66, v71
	v_div_fixup_f32 v68, v1, v68, 1.0
	v_div_scale_f32 v1, s[8:9], v69, v69, 1.0
	v_rcp_f32_e32 v66, v1
	s_nop 0
	v_fma_f32 v67, -v1, v66, 1.0
	v_fmac_f32_e32 v66, v67, v66
	v_div_scale_f32 v67, vcc, 1.0, v69, 1.0
	v_mul_f32_e32 v71, v67, v66
	v_fma_f32 v73, -v1, v71, v67
	v_fmac_f32_e32 v71, v73, v66
	v_fma_f32 v1, -v1, v71, v67
	v_div_fmas_f32 v1, v1, v66, v71
	v_div_fixup_f32 v66, v1, v69, 1.0
	s_andn2_b64 vcc, exec, s[76:77]
	s_cbranch_vccnz .LBB0_212
	v_mul_f32_e32 v1, v50, v96
	v_mul_f32_e32 v67, v34, v96
	v_mul_f32_e32 v1, v151, v1
	v_mul_f32_e32 v67, v151, v67
	ds_write2_b32 v163, v1, v67 offset1:32
	v_mul_f32_e32 v1, v18, v96
	v_mul_f32_e32 v67, v2, v96
	v_mul_f32_e32 v1, v151, v1
	v_mul_f32_e32 v67, v151, v67
	ds_write2_b32 v163, v1, v67 offset0:64 offset1:96
	v_mul_f32_e32 v1, v51, v94
	v_mul_f32_e32 v67, v35, v94
	v_mul_f32_e32 v1, v151, v1
	v_mul_f32_e32 v67, v151, v67
	ds_write2_b32 v163, v1, v67 offset0:128 offset1:160
	v_mul_f32_e32 v1, v19, v94
	v_mul_f32_e32 v67, v3, v94
	v_mul_f32_e32 v1, v151, v1
	v_mul_f32_e32 v67, v151, v67
	ds_write2_b32 v163, v1, v67 offset0:192 offset1:224
	v_mul_f32_e32 v1, v52, v92
	v_mul_f32_e32 v67, v36, v92
	v_mul_f32_e32 v1, v151, v1
	v_mul_f32_e32 v67, v151, v67
	v_add_u32_e32 v69, 0x400, v163
	ds_write2_b32 v69, v1, v67 offset1:32
	v_mul_f32_e32 v1, v20, v92
	v_mul_f32_e32 v67, v4, v92
	v_mul_f32_e32 v1, v151, v1
	v_mul_f32_e32 v67, v151, v67
	ds_write2_b32 v69, v1, v67 offset0:64 offset1:96
	v_mul_f32_e32 v1, v53, v90
	v_mul_f32_e32 v67, v37, v90
	v_mul_f32_e32 v1, v151, v1
	v_mul_f32_e32 v67, v151, v67
	ds_write2_b32 v69, v1, v67 offset0:128 offset1:160
	v_mul_f32_e32 v1, v21, v90
	v_mul_f32_e32 v67, v5, v90
	v_mul_f32_e32 v1, v151, v1
	v_mul_f32_e32 v67, v151, v67
	ds_write2_b32 v69, v1, v67 offset0:192 offset1:224
	v_mul_f32_e32 v1, v54, v88
	v_mul_f32_e32 v67, v38, v88
	v_mul_f32_e32 v1, v151, v1
	v_mul_f32_e32 v67, v151, v67
	v_add_u32_e32 v69, 0x1000, v163
	ds_write2_b32 v69, v1, v67 offset1:32
	v_mul_f32_e32 v1, v22, v88
	v_mul_f32_e32 v67, v6, v88
	v_mul_f32_e32 v1, v151, v1
	v_mul_f32_e32 v67, v151, v67
	ds_write2_b32 v69, v1, v67 offset0:64 offset1:96
	v_mul_f32_e32 v1, v55, v86
	v_mul_f32_e32 v67, v39, v86
	v_mul_f32_e32 v1, v151, v1
	v_mul_f32_e32 v67, v151, v67
	ds_write2_b32 v69, v1, v67 offset0:128 offset1:160
	v_mul_f32_e32 v1, v23, v86
	v_mul_f32_e32 v67, v7, v86
	v_mul_f32_e32 v1, v151, v1
	v_mul_f32_e32 v67, v151, v67
	ds_write2_b32 v69, v1, v67 offset0:192 offset1:224
	v_mul_f32_e32 v1, v56, v84
	v_mul_f32_e32 v67, v40, v84
	v_mul_f32_e32 v1, v151, v1
	v_mul_f32_e32 v67, v151, v67
	v_add_u32_e32 v69, 0x1400, v163
	ds_write2_b32 v69, v1, v67 offset1:32
	v_mul_f32_e32 v1, v24, v84
	v_mul_f32_e32 v67, v8, v84
	v_mul_f32_e32 v1, v151, v1
	v_mul_f32_e32 v67, v151, v67
	ds_write2_b32 v69, v1, v67 offset0:64 offset1:96
	v_mul_f32_e32 v1, v57, v82
	v_mul_f32_e32 v67, v41, v82
	v_mul_f32_e32 v1, v151, v1
	v_mul_f32_e32 v67, v151, v67
	ds_write2_b32 v69, v1, v67 offset0:128 offset1:160
	v_mul_f32_e32 v1, v25, v82
	v_mul_f32_e32 v67, v9, v82
	v_mul_f32_e32 v1, v151, v1
	v_mul_f32_e32 v67, v151, v67
	ds_write2_b32 v69, v1, v67 offset0:192 offset1:224
	v_mul_f32_e32 v1, v58, v80
	v_mul_f32_e32 v67, v42, v80
	v_mul_f32_e32 v1, v151, v1
	v_mul_f32_e32 v67, v151, v67
	v_add_u32_e32 v69, 0x2000, v163
	ds_write2_b32 v69, v1, v67 offset1:32
	v_mul_f32_e32 v1, v26, v80
	v_mul_f32_e32 v67, v10, v80
	v_mul_f32_e32 v1, v151, v1
	v_mul_f32_e32 v67, v151, v67
	ds_write2_b32 v69, v1, v67 offset0:64 offset1:96
	v_mul_f32_e32 v1, v59, v76
	v_mul_f32_e32 v67, v43, v76
	v_mul_f32_e32 v1, v151, v1
	v_mul_f32_e32 v67, v151, v67
	ds_write2_b32 v69, v1, v67 offset0:128 offset1:160
	v_mul_f32_e32 v1, v27, v76
	v_mul_f32_e32 v67, v11, v76
	v_mul_f32_e32 v1, v151, v1
	v_mul_f32_e32 v67, v151, v67
	ds_write2_b32 v69, v1, v67 offset0:192 offset1:224
	v_mul_f32_e32 v1, v60, v72
	v_mul_f32_e32 v67, v44, v72
	v_mul_f32_e32 v1, v151, v1
	v_mul_f32_e32 v67, v151, v67
	v_add_u32_e32 v69, 0x2400, v163
	ds_write2_b32 v69, v1, v67 offset1:32
	v_mul_f32_e32 v1, v28, v72
	v_mul_f32_e32 v67, v12, v72
	v_mul_f32_e32 v1, v151, v1
	v_mul_f32_e32 v67, v151, v67
	ds_write2_b32 v69, v1, v67 offset0:64 offset1:96
	v_mul_f32_e32 v1, v61, v70
	v_mul_f32_e32 v67, v45, v70
	v_mul_f32_e32 v1, v151, v1
	v_mul_f32_e32 v67, v151, v67
	ds_write2_b32 v69, v1, v67 offset0:128 offset1:160
	v_mul_f32_e32 v1, v29, v70
	v_mul_f32_e32 v67, v13, v70
	v_mul_f32_e32 v1, v151, v1
	v_mul_f32_e32 v67, v151, v67
	ds_write2_b32 v69, v1, v67 offset0:192 offset1:224
	v_mul_f32_e32 v1, v62, v78
	v_mul_f32_e32 v67, v46, v78
	v_mul_f32_e32 v1, v151, v1
	v_mul_f32_e32 v67, v151, v67
	v_add_u32_e32 v69, 0x3000, v163
	ds_write2_b32 v69, v1, v67 offset1:32
	v_mul_f32_e32 v1, v30, v78
	v_mul_f32_e32 v67, v14, v78
	v_mul_f32_e32 v1, v151, v1
	v_mul_f32_e32 v67, v151, v67
	ds_write2_b32 v69, v1, v67 offset0:64 offset1:96
	v_mul_f32_e32 v1, v63, v74
	v_mul_f32_e32 v67, v47, v74
	v_mul_f32_e32 v1, v151, v1
	v_mul_f32_e32 v67, v151, v67
	ds_write2_b32 v69, v1, v67 offset0:128 offset1:160
	v_mul_f32_e32 v1, v31, v74
	v_mul_f32_e32 v67, v15, v74
	v_mul_f32_e32 v1, v151, v1
	v_mul_f32_e32 v67, v151, v67
	ds_write2_b32 v69, v1, v67 offset0:192 offset1:224
	v_mul_f32_e32 v1, v64, v68
	v_mul_f32_e32 v67, v48, v68
	v_mul_f32_e32 v1, v151, v1
	v_mul_f32_e32 v67, v151, v67
	v_add_u32_e32 v69, 0x3400, v163
	ds_write2_b32 v69, v1, v67 offset1:32
	v_mul_f32_e32 v1, v32, v68
	v_mul_f32_e32 v67, v16, v68
	v_mul_f32_e32 v1, v151, v1
	v_mul_f32_e32 v67, v151, v67
	ds_write2_b32 v69, v1, v67 offset0:64 offset1:96
	v_mul_f32_e32 v1, v65, v66
	v_mul_f32_e32 v67, v49, v66
	v_mul_f32_e32 v1, v151, v1
	v_mul_f32_e32 v67, v151, v67
	ds_write2_b32 v69, v1, v67 offset0:128 offset1:160
	v_mul_f32_e32 v1, v33, v66
	v_mul_f32_e32 v67, v17, v66
	v_mul_f32_e32 v1, v151, v1
	v_mul_f32_e32 v67, v151, v67
	ds_write2_b32 v69, v1, v67 offset0:192 offset1:224
